# prune threshold search skips the bits shared by all list entries; intermediate prunes stop at any bit once 256..320 entries remain
# speedup vs baseline: 1.0850x; 1.0120x over previous
; #define LAS __attribute__((address_space(3)))
; template <bool FINAL>
; __device__ __forceinline__ void dsa_prune(LAS unsigned* cs, LAS unsigned short* ci, LAS unsigned* cnt, LAS float* thr, int q, int lane) {
;     const int n = __builtin_amdgcn_readfirstlane((int)cnt[q]);
;     if (n <= 256) return;
;     LAS unsigned* c = cs + q * CAP; LAS unsigned short* ix = ci + q * CAP;
;     constexpr int NE = CAP / 64;
;     unsigned x[NE];
; #pragma unroll
;     for (int i = 0; i < NE; ++i) { const int e = i * 64 + lane; x[i] = e < n ? c[e] : 0u; }
;     unsigned prefix = 0u; int kp = n;
;     ...
; #pragma unroll
;         for (int i = 0; i < NE; ++i) k += __popcll(__ballot(x[i] >= trial));
;         if (k >= 256) { prefix = trial; kp = k; }
;         if (kp == 256 || (!FINAL && bit <= 16 && kp <= 320)) break; }
.LBB0_1001:
	s_waitcnt lgkmcnt(0)
	s_barrier
	ds_read_b32 v34, v110
	s_waitcnt lgkmcnt(0)
	v_cmp_lt_u32_e32 vcc, s75, v34
	s_cmp_lg_u64 vcc, 0
	s_cselect_b64 s[42:43], -1, 0
	s_cbranch_vccz .LBB0_1214
	v_mov_b32_e32 v34, s66
	ds_read_b32 v34, v34
	s_waitcnt lgkmcnt(0)
	v_readfirstlane_b32 s73, v34
	s_cmpk_lt_i32 s73, 0x101
	s_cbranch_scc1 .LBB0_1108
	ds_read2st64_b32 v[36:37], v108 offset1:1
	ds_read2st64_b32 v[34:35], v108 offset0:2 offset1:3
	v_cmp_gt_u32_e64 s[40:41], s73, v106
	v_mov_b32_e32 v51, 0
	v_mov_b32_e32 v52, 0
	s_and_saveexec_b64 s[10:11], s[40:41]
	ds_read_b32 v52, v108 offset:1024
	s_or_b64 exec, exec, s[10:11]
	v_cmp_gt_u32_e64 s[38:39], s73, v105
	s_and_saveexec_b64 s[10:11], s[38:39]
	ds_read_b32 v51, v108 offset:1280
	s_or_b64 exec, exec, s[10:11]
	v_cmp_gt_u32_e64 s[36:37], s73, v104
	v_mov_b32_e32 v49, 0
	v_mov_b32_e32 v50, 0
	s_and_saveexec_b64 s[10:11], s[36:37]
	ds_read_b32 v50, v108 offset:1536
	s_or_b64 exec, exec, s[10:11]
	v_cmp_gt_u32_e64 s[34:35], s73, v103
	s_and_saveexec_b64 s[10:11], s[34:35]
	ds_read_b32 v49, v108 offset:1792
	s_or_b64 exec, exec, s[10:11]
	v_cmp_gt_u32_e64 s[30:31], s73, v102
	v_mov_b32_e32 v47, 0
	v_mov_b32_e32 v48, 0
	s_and_saveexec_b64 s[10:11], s[30:31]
	ds_read_b32 v48, v108 offset:2048
	s_or_b64 exec, exec, s[10:11]
	v_cmp_gt_u32_e64 s[28:29], s73, v101
	s_and_saveexec_b64 s[10:11], s[28:29]
	ds_read_b32 v47, v108 offset:2304
	s_or_b64 exec, exec, s[10:11]
	v_cmp_gt_u32_e64 s[26:27], s73, v100
	v_mov_b32_e32 v45, 0
	v_mov_b32_e32 v46, 0
	s_and_saveexec_b64 s[10:11], s[26:27]
	ds_read_b32 v46, v108 offset:2560
	s_or_b64 exec, exec, s[10:11]
	v_cmp_gt_u32_e64 s[24:25], s73, v99
	s_and_saveexec_b64 s[10:11], s[24:25]
	ds_read_b32 v45, v108 offset:2816
	s_or_b64 exec, exec, s[10:11]
	v_cmp_gt_u32_e64 s[22:23], s73, v98
	v_mov_b32_e32 v43, 0
	v_mov_b32_e32 v44, 0
	s_and_saveexec_b64 s[10:11], s[22:23]
	ds_read_b32 v44, v108 offset:3072
	s_or_b64 exec, exec, s[10:11]
	v_cmp_gt_u32_e64 s[20:21], s73, v97
	s_and_saveexec_b64 s[10:11], s[20:21]
	ds_read_b32 v43, v108 offset:3328
	s_or_b64 exec, exec, s[10:11]
	v_cmp_gt_u32_e64 s[18:19], s73, v96
	v_mov_b32_e32 v41, 0
	v_mov_b32_e32 v42, 0
	s_and_saveexec_b64 s[10:11], s[18:19]
	ds_read_b32 v42, v108 offset:3584
	s_or_b64 exec, exec, s[10:11]
	v_cmp_gt_u32_e64 s[16:17], s73, v93
	s_and_saveexec_b64 s[10:11], s[16:17]
	ds_read_b32 v41, v108 offset:3840
	s_or_b64 exec, exec, s[10:11]
	v_cmp_gt_u32_e64 s[14:15], s73, v92
	v_mov_b32_e32 v39, 0
	v_mov_b32_e32 v40, 0
	s_and_saveexec_b64 s[10:11], s[14:15]
	ds_read_b32 v40, v108 offset:4096
	s_or_b64 exec, exec, s[10:11]
	v_cmp_gt_u32_e64 s[12:13], s73, v91
	s_and_saveexec_b64 s[10:11], s[12:13]
	ds_read_b32 v39, v108 offset:4352
	s_or_b64 exec, exec, s[10:11]
	v_cmp_gt_u32_e64 s[10:11], s73, v89
	v_mov_b32_e32 v38, 0
	s_and_saveexec_b64 s[90:91], s[10:11]
	ds_read_b32 v38, v108 offset:4608
	s_or_b64 exec, exec, s[90:91]
	s_mov_b32 s99, s73
	v_mov_b32_e32 v208, s72
	ds_read_b32 v208, v208
	s_waitcnt lgkmcnt(0)
	v_or3_b32 v209, v36, v37, v34
	v_or3_b32 v209, v209, v35, v52
	v_or3_b32 v209, v209, v51, v50
	v_or3_b32 v209, v209, v49, v48
	v_or3_b32 v209, v209, v47, v46
	v_or3_b32 v209, v209, v45, v44
	v_or3_b32 v209, v209, v43, v42
	v_or3_b32 v209, v209, v41, v40
	v_or3_b32 v209, v209, v39, v38
	s_nop 1
	v_or_b32_dpp v209, v209, v209 row_shr:1 row_mask:0xf bank_mask:0xf
	s_nop 1
	v_or_b32_dpp v209, v209, v209 row_shr:2 row_mask:0xf bank_mask:0xf
	s_nop 1
	v_or_b32_dpp v209, v209, v209 row_shr:4 row_mask:0xf bank_mask:0xf
	s_nop 1
	v_or_b32_dpp v209, v209, v209 row_shr:8 row_mask:0xf bank_mask:0xf
	s_nop 1
	v_or_b32_dpp v209, v209, v209 row_bcast:15 row_mask:0xa bank_mask:0xf
	s_nop 1
	v_or_b32_dpp v209, v209, v209 row_bcast:31 row_mask:0xc bank_mask:0xf
	s_nop 0
	v_readlane_b32 s100, v209, 63
	v_readfirstlane_b32 s101, v208
	s_ashr_i32 s93, s101, 31
	s_or_b32 s93, s93, 0x80000000
	s_xor_b32 s101, s101, s93
	s_xor_b32 s93, s101, s100
	s_flbit_i32_b32 s98, s93
	s_sub_i32 s98, 31, s98
	s_cmp_eq_u32 s93, 0
	s_cselect_b32 s98, 31, s98
	s_cselect_b32 s100, 0, s100
	s_lshl_b32 s93, 2, s98
	s_sub_u32 s93, s93, 1
	s_andn2_b32 s70, s100, s93
	s_mov_b32 s92, s98
	s_branch .LBB0_1035

; template <bool FINAL>
; __device__ __forceinline__ void dsa_prune(LAS unsigned* cs, LAS unsigned short* ci, LAS unsigned* cnt, LAS float* thr, int q, int lane) {
;     ...
; #pragma unroll
;         for (int i = 0; i < NE; ++i) k += __popcll(__ballot(x[i] >= trial));
;         if (k >= 256) { prefix = trial; kp = k; }
;         if (kp == 256 || (!FINAL && bit <= 16 && kp <= 320)) break; }
.Lps_done_a:
	s_cmpk_gt_u32 s79, 0xff
	s_cselect_b32 s73, s79, s73
	s_cselect_b32 s70, s78, s70
	s_cmpk_eq_i32 s73, 0x100
	s_mov_b64 s[90:91], -1
	s_cbranch_scc1 .LBB0_1034
	s_cmp_lt_u32 s92, 32
	s_cselect_b64 s[90:91], -1, 0
	s_cmpk_lt_i32 s73, 0x141
	s_cselect_b64 vcc, -1, 0
	s_and_b64 s[90:91], s[90:91], vcc
	v_sub_co_u32_e64 v53, vcc, s92, 1
	s_nop 0
	v_readfirstlane_b32 s92, v53
	s_or_b64 s[90:91], vcc, s[90:91]
	s_branch .LBB0_1034

; #define LAS __attribute__((address_space(3)))
; template <bool FINAL>
; __device__ __forceinline__ void dsa_prune(LAS unsigned* cs, LAS unsigned short* ci, LAS unsigned* cnt, LAS float* thr, int q, int lane) {
;     const int n = __builtin_amdgcn_readfirstlane((int)cnt[q]);
;     if (n <= 256) return;
;     LAS unsigned* c = cs + q * CAP; LAS unsigned short* ix = ci + q * CAP;
;     constexpr int NE = CAP / 64;
;     unsigned x[NE];
; #pragma unroll
;     for (int i = 0; i < NE; ++i) { const int e = i * 64 + lane; x[i] = e < n ? c[e] : 0u; }
;     unsigned prefix = 0u; int kp = n;
;     ...
; #pragma unroll
;         for (int i = 0; i < NE; ++i) k += __popcll(__ballot(x[i] >= trial));
;         if (k >= 256) { prefix = trial; kp = k; }
;         if (kp == 256 || (!FINAL && bit <= 16 && kp <= 320)) break; }
.LBB0_1108:
	s_waitcnt lgkmcnt(0)
	v_mov_b32_e32 v34, s59
	ds_read_b32 v34, v34
	s_waitcnt lgkmcnt(0)
	v_readfirstlane_b32 s73, v34
	s_cmpk_lt_i32 s73, 0x101
	s_cbranch_scc1 .LBB0_1214
	ds_read2st64_b32 v[36:37], v90 offset1:1
	ds_read2st64_b32 v[34:35], v90 offset0:2 offset1:3
	v_cmp_gt_u32_e64 s[40:41], s73, v106
	v_mov_b32_e32 v51, 0
	v_mov_b32_e32 v52, 0
	s_and_saveexec_b64 s[10:11], s[40:41]
	ds_read_b32 v52, v90 offset:1024
	s_or_b64 exec, exec, s[10:11]
	v_cmp_gt_u32_e64 s[38:39], s73, v105
	s_and_saveexec_b64 s[10:11], s[38:39]
	ds_read_b32 v51, v90 offset:1280
	s_or_b64 exec, exec, s[10:11]
	v_cmp_gt_u32_e64 s[36:37], s73, v104
	v_mov_b32_e32 v49, 0
	v_mov_b32_e32 v50, 0
	s_and_saveexec_b64 s[10:11], s[36:37]
	ds_read_b32 v50, v90 offset:1536
	s_or_b64 exec, exec, s[10:11]
	v_cmp_gt_u32_e64 s[34:35], s73, v103
	s_and_saveexec_b64 s[10:11], s[34:35]
	ds_read_b32 v49, v90 offset:1792
	s_or_b64 exec, exec, s[10:11]
	v_cmp_gt_u32_e64 s[30:31], s73, v102
	v_mov_b32_e32 v47, 0
	v_mov_b32_e32 v48, 0
	s_and_saveexec_b64 s[10:11], s[30:31]
	ds_read_b32 v48, v90 offset:2048
	s_or_b64 exec, exec, s[10:11]
	v_cmp_gt_u32_e64 s[28:29], s73, v101
	s_and_saveexec_b64 s[10:11], s[28:29]
	ds_read_b32 v47, v90 offset:2304
	s_or_b64 exec, exec, s[10:11]
	v_cmp_gt_u32_e64 s[26:27], s73, v100
	v_mov_b32_e32 v45, 0
	v_mov_b32_e32 v46, 0
	s_and_saveexec_b64 s[10:11], s[26:27]
	ds_read_b32 v46, v90 offset:2560
	s_or_b64 exec, exec, s[10:11]
	v_cmp_gt_u32_e64 s[24:25], s73, v99
	s_and_saveexec_b64 s[10:11], s[24:25]
	ds_read_b32 v45, v90 offset:2816
	s_or_b64 exec, exec, s[10:11]
	v_cmp_gt_u32_e64 s[22:23], s73, v98
	v_mov_b32_e32 v43, 0
	v_mov_b32_e32 v44, 0
	s_and_saveexec_b64 s[10:11], s[22:23]
	ds_read_b32 v44, v90 offset:3072
	s_or_b64 exec, exec, s[10:11]
	v_cmp_gt_u32_e64 s[20:21], s73, v97
	s_and_saveexec_b64 s[10:11], s[20:21]
	ds_read_b32 v43, v90 offset:3328
	s_or_b64 exec, exec, s[10:11]
	v_cmp_gt_u32_e64 s[18:19], s73, v96
	v_mov_b32_e32 v41, 0
	v_mov_b32_e32 v42, 0
	s_and_saveexec_b64 s[10:11], s[18:19]
	ds_read_b32 v42, v90 offset:3584
	s_or_b64 exec, exec, s[10:11]
	v_cmp_gt_u32_e64 s[16:17], s73, v93
	s_and_saveexec_b64 s[10:11], s[16:17]
	ds_read_b32 v41, v90 offset:3840
	s_or_b64 exec, exec, s[10:11]
	v_cmp_gt_u32_e64 s[14:15], s73, v92
	v_mov_b32_e32 v39, 0
	v_mov_b32_e32 v40, 0
	s_and_saveexec_b64 s[10:11], s[14:15]
	ds_read_b32 v40, v90 offset:4096
	s_or_b64 exec, exec, s[10:11]
	v_cmp_gt_u32_e64 s[12:13], s73, v91
	s_and_saveexec_b64 s[10:11], s[12:13]
	ds_read_b32 v39, v90 offset:4352
	s_or_b64 exec, exec, s[10:11]
	v_cmp_gt_u32_e64 s[10:11], s73, v89
	v_mov_b32_e32 v38, 0
	s_and_saveexec_b64 s[90:91], s[10:11]
	ds_read_b32 v38, v90 offset:4608
	s_or_b64 exec, exec, s[90:91]
	s_mov_b32 s99, s73
	v_mov_b32_e32 v208, s74
	ds_read_b32 v208, v208
	s_waitcnt lgkmcnt(0)
	v_or3_b32 v209, v36, v37, v34
	v_or3_b32 v209, v209, v35, v52
	v_or3_b32 v209, v209, v51, v50
	v_or3_b32 v209, v209, v49, v48
	v_or3_b32 v209, v209, v47, v46
	v_or3_b32 v209, v209, v45, v44
	v_or3_b32 v209, v209, v43, v42
	v_or3_b32 v209, v209, v41, v40
	v_or3_b32 v209, v209, v39, v38
	s_nop 1
	v_or_b32_dpp v209, v209, v209 row_shr:1 row_mask:0xf bank_mask:0xf
	s_nop 1
	v_or_b32_dpp v209, v209, v209 row_shr:2 row_mask:0xf bank_mask:0xf
	s_nop 1
	v_or_b32_dpp v209, v209, v209 row_shr:4 row_mask:0xf bank_mask:0xf
	s_nop 1
	v_or_b32_dpp v209, v209, v209 row_shr:8 row_mask:0xf bank_mask:0xf
	s_nop 1
	v_or_b32_dpp v209, v209, v209 row_bcast:15 row_mask:0xa bank_mask:0xf
	s_nop 1
	v_or_b32_dpp v209, v209, v209 row_bcast:31 row_mask:0xc bank_mask:0xf
	s_nop 0
	v_readlane_b32 s100, v209, 63
	v_readfirstlane_b32 s101, v208
	s_ashr_i32 s93, s101, 31
	s_or_b32 s93, s93, 0x80000000
	s_xor_b32 s101, s101, s93
	s_xor_b32 s93, s101, s100
	s_flbit_i32_b32 s98, s93
	s_sub_i32 s98, 31, s98
	s_cmp_eq_u32 s93, 0
	s_cselect_b32 s98, 31, s98
	s_cselect_b32 s100, 0, s100
	s_lshl_b32 s93, 2, s98
	s_sub_u32 s93, s93, 1
	s_andn2_b32 s70, s100, s93
	s_mov_b32 s92, s98
	s_branch .LBB0_1141

; #define LAS __attribute__((address_space(3)))
; template <bool FINAL>
; __device__ __forceinline__ void dsa_prune(LAS unsigned* cs, LAS unsigned short* ci, LAS unsigned* cnt, LAS float* thr, int q, int lane) {
;     const int n = __builtin_amdgcn_readfirstlane((int)cnt[q]);
;     if (n <= 256) return;
;     LAS unsigned* c = cs + q * CAP; LAS unsigned short* ix = ci + q * CAP;
;     constexpr int NE = CAP / 64;
;     unsigned x[NE];
; #pragma unroll
;     for (int i = 0; i < NE; ++i) { const int e = i * 64 + lane; x[i] = e < n ? c[e] : 0u; }
;     unsigned prefix = 0u; int kp = n;
;     ...
; #pragma unroll
;         for (int i = 0; i < NE; ++i) k += __popcll(__ballot(x[i] >= trial));
;         if (k >= 256) { prefix = trial; kp = k; }
;         if (kp == 256 || (!FINAL && bit <= 16 && kp <= 320)) break; }
.LBB0_1219:
	s_or_b64 exec, exec, s[10:11]
	v_mov_b32_e32 v2, s66
	ds_read_b32 v2, v2
	v_readlane_b32 s79, v236, 39
	s_movk_i32 s96, 0x100
	s_waitcnt lgkmcnt(0)
	v_readfirstlane_b32 s1, v2
	s_cmpk_lt_i32 s1, 0x101
	s_cbranch_scc1 .LBB0_1323
	ds_read2st64_b32 v[4:5], v108 offset1:1
	ds_read2st64_b32 v[2:3], v108 offset0:2 offset1:3
	v_cmp_gt_u32_e64 s[40:41], s1, v106
	v_mov_b32_e32 v19, 0
	v_mov_b32_e32 v20, 0
	s_and_saveexec_b64 s[10:11], s[40:41]
	ds_read_b32 v20, v108 offset:1024
	s_or_b64 exec, exec, s[10:11]
	v_cmp_gt_u32_e64 s[38:39], s1, v105
	s_and_saveexec_b64 s[10:11], s[38:39]
	ds_read_b32 v19, v108 offset:1280
	s_or_b64 exec, exec, s[10:11]
	v_cmp_gt_u32_e64 s[36:37], s1, v104
	v_mov_b32_e32 v17, 0
	v_mov_b32_e32 v18, 0
	s_and_saveexec_b64 s[10:11], s[36:37]
	ds_read_b32 v18, v108 offset:1536
	s_or_b64 exec, exec, s[10:11]
	v_cmp_gt_u32_e64 s[34:35], s1, v103
	s_and_saveexec_b64 s[10:11], s[34:35]
	ds_read_b32 v17, v108 offset:1792
	s_or_b64 exec, exec, s[10:11]
	v_cmp_gt_u32_e64 s[30:31], s1, v102
	v_mov_b32_e32 v15, 0
	v_mov_b32_e32 v16, 0
	s_and_saveexec_b64 s[10:11], s[30:31]
	ds_read_b32 v16, v108 offset:2048
	s_or_b64 exec, exec, s[10:11]
	v_cmp_gt_u32_e64 s[28:29], s1, v101
	s_and_saveexec_b64 s[10:11], s[28:29]
	ds_read_b32 v15, v108 offset:2304
	s_or_b64 exec, exec, s[10:11]
	v_cmp_gt_u32_e64 s[26:27], s1, v100
	v_mov_b32_e32 v13, 0
	v_mov_b32_e32 v14, 0
	s_and_saveexec_b64 s[10:11], s[26:27]
	ds_read_b32 v14, v108 offset:2560
	s_or_b64 exec, exec, s[10:11]
	v_cmp_gt_u32_e64 s[24:25], s1, v99
	s_and_saveexec_b64 s[10:11], s[24:25]
	ds_read_b32 v13, v108 offset:2816
	s_or_b64 exec, exec, s[10:11]
	v_cmp_gt_u32_e64 s[22:23], s1, v98
	v_mov_b32_e32 v11, 0
	v_mov_b32_e32 v12, 0
	s_and_saveexec_b64 s[10:11], s[22:23]
	ds_read_b32 v12, v108 offset:3072
	s_or_b64 exec, exec, s[10:11]
	v_cmp_gt_u32_e64 s[20:21], s1, v97
	s_and_saveexec_b64 s[10:11], s[20:21]
	ds_read_b32 v11, v108 offset:3328
	s_or_b64 exec, exec, s[10:11]
	v_cmp_gt_u32_e64 s[18:19], s1, v96
	v_mov_b32_e32 v9, 0
	v_mov_b32_e32 v10, 0
	s_and_saveexec_b64 s[10:11], s[18:19]
	ds_read_b32 v10, v108 offset:3584
	s_or_b64 exec, exec, s[10:11]
	v_cmp_gt_u32_e64 s[16:17], s1, v93
	s_and_saveexec_b64 s[10:11], s[16:17]
	ds_read_b32 v9, v108 offset:3840
	s_or_b64 exec, exec, s[10:11]
	v_cmp_gt_u32_e64 s[14:15], s1, v92
	v_mov_b32_e32 v7, 0
	v_mov_b32_e32 v8, 0
	s_and_saveexec_b64 s[10:11], s[14:15]
	ds_read_b32 v8, v108 offset:4096
	s_or_b64 exec, exec, s[10:11]
	v_cmp_gt_u32_e64 s[12:13], s1, v91
	s_and_saveexec_b64 s[10:11], s[12:13]
	ds_read_b32 v7, v108 offset:4352
	s_or_b64 exec, exec, s[10:11]
	v_cmp_gt_u32_e64 s[10:11], s1, v89
	v_mov_b32_e32 v6, 0
	s_and_saveexec_b64 s[42:43], s[10:11]
	ds_read_b32 v6, v108 offset:4608
	s_or_b64 exec, exec, s[42:43]
	s_mov_b32 s99, s1
	v_mov_b32_e32 v208, s72
	ds_read_b32 v208, v208
	s_waitcnt lgkmcnt(0)
	v_or3_b32 v209, v4, v5, v2
	v_or3_b32 v209, v209, v3, v20
	v_or3_b32 v209, v209, v19, v18
	v_or3_b32 v209, v209, v17, v16
	v_or3_b32 v209, v209, v15, v14
	v_or3_b32 v209, v209, v13, v12
	v_or3_b32 v209, v209, v11, v10
	v_or3_b32 v209, v209, v9, v8
	v_or3_b32 v209, v209, v7, v6
	s_nop 1
	v_or_b32_dpp v209, v209, v209 row_shr:1 row_mask:0xf bank_mask:0xf
	s_nop 1
	v_or_b32_dpp v209, v209, v209 row_shr:2 row_mask:0xf bank_mask:0xf
	s_nop 1
	v_or_b32_dpp v209, v209, v209 row_shr:4 row_mask:0xf bank_mask:0xf
	s_nop 1
	v_or_b32_dpp v209, v209, v209 row_shr:8 row_mask:0xf bank_mask:0xf
	s_nop 1
	v_or_b32_dpp v209, v209, v209 row_bcast:15 row_mask:0xa bank_mask:0xf
	s_nop 1
	v_or_b32_dpp v209, v209, v209 row_bcast:31 row_mask:0xc bank_mask:0xf
	s_nop 0
	v_readlane_b32 s100, v209, 63
	v_readfirstlane_b32 s101, v208
	s_ashr_i32 s93, s101, 31
	s_or_b32 s93, s93, 0x80000000
	s_xor_b32 s101, s101, s93
	s_xor_b32 s93, s101, s100
	s_flbit_i32_b32 s98, s93
	s_sub_i32 s98, 31, s98
	s_cmp_eq_u32 s93, 0
	s_cselect_b32 s98, 31, s98
	s_cselect_b32 s100, 0, s100
	s_lshl_b32 s93, 2, s98
	s_sub_u32 s93, s93, 1
	s_andn2_b32 s0, s100, s93
	s_mov_b32 s70, s98

; #define LAS __attribute__((address_space(3)))
; template <bool FINAL>
; __device__ __forceinline__ void dsa_prune(LAS unsigned* cs, LAS unsigned short* ci, LAS unsigned* cnt, LAS float* thr, int q, int lane) {
;     const int n = __builtin_amdgcn_readfirstlane((int)cnt[q]);
;     if (n <= 256) return;
;     LAS unsigned* c = cs + q * CAP; LAS unsigned short* ix = ci + q * CAP;
;     constexpr int NE = CAP / 64;
;     unsigned x[NE];
; #pragma unroll
;     for (int i = 0; i < NE; ++i) { const int e = i * 64 + lane; x[i] = e < n ? c[e] : 0u; }
;     unsigned prefix = 0u; int kp = n;
;     ...
; #pragma unroll
;         for (int i = 0; i < NE; ++i) k += __popcll(__ballot(x[i] >= trial));
;         if (k >= 256) { prefix = trial; kp = k; }
;         if (kp == 256 || (!FINAL && bit <= 16 && kp <= 320)) break; }
.LBB0_1323:
	s_waitcnt lgkmcnt(0)
	v_mov_b32_e32 v2, s59
	ds_read_b32 v2, v2
	s_waitcnt lgkmcnt(0)
	v_readfirstlane_b32 s1, v2
	s_cmpk_lt_i32 s1, 0x101
	s_cbranch_scc1 .LBB0_1427
	ds_read2st64_b32 v[4:5], v90 offset1:1
	ds_read2st64_b32 v[2:3], v90 offset0:2 offset1:3
	v_cmp_gt_u32_e64 s[40:41], s1, v106
	v_mov_b32_e32 v19, 0
	v_mov_b32_e32 v20, 0
	s_and_saveexec_b64 s[10:11], s[40:41]
	ds_read_b32 v20, v90 offset:1024
	s_or_b64 exec, exec, s[10:11]
	v_cmp_gt_u32_e64 s[38:39], s1, v105
	s_and_saveexec_b64 s[10:11], s[38:39]
	ds_read_b32 v19, v90 offset:1280
	s_or_b64 exec, exec, s[10:11]
	v_cmp_gt_u32_e64 s[36:37], s1, v104
	v_mov_b32_e32 v17, 0
	v_mov_b32_e32 v18, 0
	s_and_saveexec_b64 s[10:11], s[36:37]
	ds_read_b32 v18, v90 offset:1536
	s_or_b64 exec, exec, s[10:11]
	v_cmp_gt_u32_e64 s[34:35], s1, v103
	s_and_saveexec_b64 s[10:11], s[34:35]
	ds_read_b32 v17, v90 offset:1792
	s_or_b64 exec, exec, s[10:11]
	v_cmp_gt_u32_e64 s[30:31], s1, v102
	v_mov_b32_e32 v15, 0
	v_mov_b32_e32 v16, 0
	s_and_saveexec_b64 s[10:11], s[30:31]
	ds_read_b32 v16, v90 offset:2048
	s_or_b64 exec, exec, s[10:11]
	v_cmp_gt_u32_e64 s[28:29], s1, v101
	s_and_saveexec_b64 s[10:11], s[28:29]
	ds_read_b32 v15, v90 offset:2304
	s_or_b64 exec, exec, s[10:11]
	v_cmp_gt_u32_e64 s[26:27], s1, v100
	v_mov_b32_e32 v13, 0
	v_mov_b32_e32 v14, 0
	s_and_saveexec_b64 s[10:11], s[26:27]
	ds_read_b32 v14, v90 offset:2560
	s_or_b64 exec, exec, s[10:11]
	v_cmp_gt_u32_e64 s[24:25], s1, v99
	s_and_saveexec_b64 s[10:11], s[24:25]
	ds_read_b32 v13, v90 offset:2816
	s_or_b64 exec, exec, s[10:11]
	v_cmp_gt_u32_e64 s[22:23], s1, v98
	v_mov_b32_e32 v11, 0
	v_mov_b32_e32 v12, 0
	s_and_saveexec_b64 s[10:11], s[22:23]
	ds_read_b32 v12, v90 offset:3072
	s_or_b64 exec, exec, s[10:11]
	v_cmp_gt_u32_e64 s[20:21], s1, v97
	s_and_saveexec_b64 s[10:11], s[20:21]
	ds_read_b32 v11, v90 offset:3328
	s_or_b64 exec, exec, s[10:11]
	v_cmp_gt_u32_e64 s[18:19], s1, v96
	v_mov_b32_e32 v9, 0
	v_mov_b32_e32 v10, 0
	s_and_saveexec_b64 s[10:11], s[18:19]
	ds_read_b32 v10, v90 offset:3584
	s_or_b64 exec, exec, s[10:11]
	v_cmp_gt_u32_e64 s[16:17], s1, v93
	s_and_saveexec_b64 s[10:11], s[16:17]
	ds_read_b32 v9, v90 offset:3840
	s_or_b64 exec, exec, s[10:11]
	v_cmp_gt_u32_e64 s[14:15], s1, v92
	v_mov_b32_e32 v7, 0
	v_mov_b32_e32 v8, 0
	s_and_saveexec_b64 s[10:11], s[14:15]
	ds_read_b32 v8, v90 offset:4096
	s_or_b64 exec, exec, s[10:11]
	v_cmp_gt_u32_e64 s[12:13], s1, v91
	s_and_saveexec_b64 s[10:11], s[12:13]
	ds_read_b32 v7, v90 offset:4352
	s_or_b64 exec, exec, s[10:11]
	v_cmp_gt_u32_e64 s[10:11], s1, v89
	v_mov_b32_e32 v6, 0
	s_and_saveexec_b64 s[42:43], s[10:11]
	ds_read_b32 v6, v90 offset:4608
	s_or_b64 exec, exec, s[42:43]
	s_mov_b32 s99, s1
	v_mov_b32_e32 v208, s74
	ds_read_b32 v208, v208
	s_waitcnt lgkmcnt(0)
	v_or3_b32 v209, v4, v5, v2
	v_or3_b32 v209, v209, v3, v20
	v_or3_b32 v209, v209, v19, v18
	v_or3_b32 v209, v209, v17, v16
	v_or3_b32 v209, v209, v15, v14
	v_or3_b32 v209, v209, v13, v12
	v_or3_b32 v209, v209, v11, v10
	v_or3_b32 v209, v209, v9, v8
	v_or3_b32 v209, v209, v7, v6
	s_nop 1
	v_or_b32_dpp v209, v209, v209 row_shr:1 row_mask:0xf bank_mask:0xf
	s_nop 1
	v_or_b32_dpp v209, v209, v209 row_shr:2 row_mask:0xf bank_mask:0xf
	s_nop 1
	v_or_b32_dpp v209, v209, v209 row_shr:4 row_mask:0xf bank_mask:0xf
	s_nop 1
	v_or_b32_dpp v209, v209, v209 row_shr:8 row_mask:0xf bank_mask:0xf
	s_nop 1
	v_or_b32_dpp v209, v209, v209 row_bcast:15 row_mask:0xa bank_mask:0xf
	s_nop 1
	v_or_b32_dpp v209, v209, v209 row_bcast:31 row_mask:0xc bank_mask:0xf
	s_nop 0
	v_readlane_b32 s100, v209, 63
	v_readfirstlane_b32 s101, v208
	s_ashr_i32 s93, s101, 31
	s_or_b32 s93, s93, 0x80000000
	s_xor_b32 s101, s101, s93
	s_xor_b32 s93, s101, s100
	s_flbit_i32_b32 s98, s93
	s_sub_i32 s98, 31, s98
	s_cmp_eq_u32 s93, 0
	s_cselect_b32 s98, 31, s98
	s_cselect_b32 s100, 0, s100
	s_lshl_b32 s93, 2, s98
	s_sub_u32 s93, s93, 1
	s_andn2_b32 s0, s100, s93
	s_mov_b32 s66, s98
